# v32 + GLA head-norm gamma/beta (loop invariant) loaded once before the chunk loop
# baseline (speedup 1.0000x reference)
; #define LAS __attribute__((address_space(3)))
; DI void gla_item(KA a, const int l, LAS unsigned char* lds, const int item) {
;     ...
;     { const float* wa2 = a->in[I_GLA_A2] + (size_t)l * 16 * 256; const float* ba = a->in[I_GLA_BA] + l * 256;
;       for (int i = tid; i < 1024; i += NTHR) WA2[i] = wa2[(i >> 6) * 256 + hh * 64 + (i & 63)];
;       if (tid < 64) BA[tid] = ba[hh * 64 + tid];
;       for (int i = tid; i < 64 * PA / 2; i += NTHR) ((LAS unsigned*)ST)[i] = 0u; }
;     const float* lnw = a->in[I_GLA_LNW] + l * 256 + hh * 64; const float* lnb = a->in[I_GLA_LNB] + l * 256 + hh * 64;
;     f32x4 S[2] = {ZERO4, ZERO4};
;     const int t = tid >> 3, kg = tid & 7, rt = w & 3, cp = (w >> 2) * 2;
;     __syncthreads();
;     v4u pq, pk_, pv_, pg_, pa0, pa1;
;     { const bf16* hr0 = H + ((size_t)b * SEQ + t) * HP; pq = *(const v4u*)(hr0 + C_GQ + hh * 64 + 8 * kg); pk_ = *(const v4u*)(hr0 + C_GK + hh * 64 + 8 * kg); pv_ = *(const v4u*)(hr0 + C_GV + hh * 64 + 8 * kg);
;       pg_ = *(const v4u*)(hr0 + C_GG + hh * 64 + 8 * kg); pa0 = *(const v4u*)(hr0 + C_GA); pa1 = *(const v4u*)(hr0 + C_GA + 8); }
.LBB0_564:
	s_or_b64 exec, exec, s[0:1]
	s_load_dwordx4 s[0:3], s[12:13], 0x28
	v_readlane_b32 s6, v254, 33
	v_readlane_b32 s7, v254, 34
	s_lshl_b64 s[6:7], s[6:7], 2
	v_readlane_b32 s9, v253, 23
	s_waitcnt lgkmcnt(0)
	s_add_u32 s0, s0, s6
	s_addc_u32 s1, s1, s7
	s_lshl_b32 s8, s9, 2
	s_add_u32 s0, s0, s8
	s_addc_u32 s1, s1, 0
	s_add_u32 s2, s2, s6
	s_addc_u32 s3, s3, s7
	s_add_u32 s6, s2, s8
	s_addc_u32 s7, s3, 0
	v_ashrrev_i32_e32 v8, 3, v4
	v_readlane_b32 s2, v253, 24
	v_ashrrev_i32_e32 v9, 31, v8
	v_readlane_b32 s3, v253, 25
	v_mov_b64_e32 v[2:3], s[4:5]
	s_movk_i32 s8, 0x1c00
	v_lshl_add_u64 v[0:1], s[2:3], 0, v[8:9]
	v_mad_u64_u32 v[2:3], s[2:3], v0, s8, v[2:3]
	v_mad_i32_i24 v3, v1, s8, v3
	s_mov_b64 s[2:3], 0x8000000
	v_lshl_add_u64 v[10:11], v[2:3], 0, s[2:3]
	v_lshlrev_b32_e32 v2, 3, v4
	s_lshl_b32 s90, s9, 1
	v_and_b32_e32 v16, 56, v2
	v_lshl_add_u64 v[0:1], v[10:11], 0, s[90:91]
	v_lshlrev_b32_e32 v192, 1, v16
	v_lshl_add_u64 v[0:1], v[0:1], 0, v[192:193]
	s_barrier
	global_load_dwordx4 v[36:39], v[0:1], off
	global_load_dwordx4 v[44:47], v[0:1], off offset:512
	global_load_dwordx4 v[40:43], v[0:1], off offset:1024
	s_nop 0
	global_load_dwordx4 v[0:3], v[0:1], off offset:1536
	s_nop 0
	global_load_dwordx4 v[48:51], v[10:11], off offset:2064
	global_load_dwordx4 v[52:55], v[10:11], off offset:2048
	v_ashrrev_i32_e32 v5, 6, v4
	v_lshlrev_b32_e32 v11, 11, v5
	v_lshlrev_b32_e32 v17, 2, v6
	v_and_b32_e32 v13, 3, v5
	v_add3_u32 v139, 0, v11, v17
	v_mul_lo_u32 v11, v8, s75
	v_and_b32_e32 v7, 15, v4
	v_add3_u32 v140, 0, v11, v192
	v_lshlrev_b32_e32 v11, 4, v13
	v_lshrrev_b32_e32 v12, 4, v6
	v_or_b32_e32 v17, v11, v7
	v_lshlrev_b32_e32 v18, 3, v12
	v_lshl_or_b32 v11, v12, 2, v11
	v_mul_u32_u24_e32 v12, 0x48, v17
	v_and_b32_e32 v6, 48, v6
	v_lshlrev_b32_e32 v12, 1, v12
	v_readlane_b32 s3, v254, 8
	v_readlane_b32 s2, v254, 7
	v_ashrrev_i32_e32 v14, 7, v4
	v_add3_u32 v144, s3, v12, v6
	v_lshl_add_u32 v12, v13, 6, 0
	v_lshlrev_b32_e32 v13, 5, v13
	v_add3_u32 v146, s2, v13, v18
	v_and_b32_e32 v18, 64, v238
	v_xor_b32_e32 v13, 1, v238
	v_add_u32_e32 v18, 64, v18
	v_cmp_lt_i32_e32 vcc, v13, v18
	v_cmp_lt_i32_e64 s[42:43], 0, v5
	v_cmp_lt_i32_e64 s[44:45], 1, v5
	v_cndmask_b32_e32 v13, v238, v13, vcc
	v_lshlrev_b32_e32 v147, 2, v13
	v_xor_b32_e32 v13, 2, v238
	v_cmp_lt_i32_e32 vcc, v13, v18
	v_cmp_lt_i32_e64 s[46:47], 2, v5
	v_cmp_lt_i32_e64 s[48:49], 3, v5
	v_cndmask_b32_e32 v13, v238, v13, vcc
	v_lshlrev_b32_e32 v148, 2, v13
	v_xor_b32_e32 v13, 4, v238
	v_cmp_lt_i32_e32 vcc, v13, v18
	v_cmp_lt_i32_e64 s[50:51], 4, v5
	v_cmp_lt_i32_e64 s[52:53], 5, v5
	v_cndmask_b32_e32 v13, v238, v13, vcc
	v_cmp_lt_i32_e64 s[54:55], 6, v5
	v_cmp_lt_i32_e64 s[56:57], 7, v5
	v_mul_u32_u24_e32 v5, 0x48, v16
	v_and_b32_e32 v15, -2, v14
	v_readlane_b32 s9, v254, 9
	v_lshlrev_b32_e32 v149, 2, v13
	v_add_lshl_u32 v5, v5, v8, 1
	v_or_b32_e32 v13, 1, v14
	v_add_u32_e32 v141, 0, v6
	v_add_u32_e32 v143, s2, v6
	v_add_u32_e32 v145, s9, v6
	v_lshl_add_u32 v6, v7, 2, 0
	v_add_u32_e32 v150, 0, v5
	v_add_u32_e32 v151, s9, v5
	v_lshl_or_b32 v5, v15, 4, v7
	v_lshl_or_b32 v7, v13, 4, v7
	v_lshlrev_b32_e32 v10, 2, v16
	v_cmp_gt_i32_e64 s[58:59], v5, v11
	v_mul_u32_u24_e32 v16, 0x90, v11
	v_or_b32_e32 v18, 1, v11
	v_or_b32_e32 v19, 2, v11
	v_or_b32_e32 v20, 3, v11
	v_cmp_gt_i32_e64 s[66:67], v7, v11
	v_lshlrev_b32_e32 v161, 8, v11
	v_mov_b32_e32 v11, v193
	v_mad_u32_u24 v142, v17, s75, v141
	v_and_b32_e32 v17, 48, v4
	v_lshl_add_u64 v[116:117], s[0:1], 0, v[10:11]
	v_readlane_b32 s0, v253, 57
	v_lshlrev_b32_e32 v4, 4, v4
	v_mul_lo_u32 v160, v7, s75
	v_lshl_add_u32 v14, v5, 1, s3
	v_lshl_add_u32 v21, v7, 1, s3
	v_cmp_gt_i32_e64 s[68:69], v7, v18
	v_cmp_gt_i32_e64 s[70:71], v7, v19
	v_cmp_gt_i32_e64 s[2:3], v7, v20
	v_lshl_add_u32 v162, v15, 6, v6
	v_lshl_add_u32 v166, v13, 6, v6
	s_add_u32 s0, s4, s0
	v_readlane_b32 s1, v253, 58
	v_lshlrev_b64 v[6:7], 11, v[8:9]
	v_and_b32_e32 v9, 0x70, v4
	s_addc_u32 s1, s5, s1
	v_or_b32_e32 v6, v6, v9
	v_lshl_add_u64 v[120:121], s[0:1], 0, v[6:7]
	v_readlane_b32 s0, v253, 63
	s_add_u32 s0, s4, s0
	v_readlane_b32 s1, v254, 1
	s_addc_u32 s1, s5, s1
	v_mul_lo_u32 v159, v5, s75
	v_mov_b64_e32 v[6:7], s[0:1]
	v_mad_i64_i32 v[122:123], s[0:1], v8, s8, v[6:7]
	v_readlane_b32 s0, v254, 0
	v_cmp_gt_i32_e64 s[60:61], v5, v18
	v_cmp_gt_i32_e64 s[62:63], v5, v19
	v_cmp_gt_i32_e64 s[64:65], v5, v20
	v_lshl_add_u64 v[118:119], s[6:7], 0, v[10:11]
	v_mad_i64_i32 v[4:5], s[6:7], v8, s8, 0
	s_add_u32 s0, s4, s0
	v_readlane_b32 s1, v254, 2
	v_add_u32_e32 v137, 0, v10
	s_addc_u32 s1, s5, s1
	v_or_b32_e32 v4, v4, v9
	v_lshl_add_u32 v138, v8, 8, v137
	v_cmp_eq_u32_e64 s[40:41], 63, v8
	v_lshlrev_b32_e32 v163, 8, v18
	v_lshlrev_b32_e32 v164, 8, v19
	v_lshlrev_b32_e32 v165, 8, v20
	v_lshl_add_u64 v[124:125], s[0:1], 0, v[4:5]
	v_mov_b32_e32 v32, 0
	v_add_u32_e32 v167, v14, v16
	v_add_u32_e32 v168, v21, v16
	v_add_u32_e32 v169, v12, v17
	s_waitcnt vmcnt(1)
	v_mov_b64_e32 v[20:21], v[48:49]
	s_waitcnt vmcnt(0)
	v_mov_b64_e32 v[24:25], v[52:53]
	v_mov_b64_e32 v[6:7], v[2:3]
	v_mov_b64_e32 v[8:9], v[40:41]
	v_mov_b64_e32 v[12:13], v[44:45]
	v_mov_b64_e32 v[16:17], v[36:37]
	v_add_u32_e32 v152, 0x90, v151
	v_add_u32_e32 v153, 0x120, v151
	v_add_u32_e32 v154, 0x1b0, v151
	v_add_u32_e32 v155, 0x240, v151
	v_add_u32_e32 v156, 0x2d0, v151
	v_add_u32_e32 v157, 0x360, v151
	v_add_u32_e32 v158, 0x3f0, v151
	s_mov_b64 s[4:5], 0
	v_mov_b32_e32 v33, v32
	v_mov_b32_e32 v34, v32
	v_mov_b32_e32 v35, v32
	v_mov_b32_e32 v28, v32
	v_mov_b32_e32 v29, v32
	v_mov_b32_e32 v30, v32
	v_mov_b32_e32 v31, v32
	v_mov_b64_e32 v[22:23], v[50:51]
	v_mov_b64_e32 v[26:27], v[54:55]
	v_mov_b64_e32 v[4:5], v[0:1]
	v_mov_b64_e32 v[10:11], v[42:43]
	v_mov_b64_e32 v[14:15], v[46:47]
	v_mov_b64_e32 v[18:19], v[38:39]
	global_load_dwordx4 v[208:211], v[116:117], off offset:16
	global_load_dwordx4 v[212:215], v[116:117], off
	global_load_dwordx4 v[216:219], v[118:119], off offset:16
	global_load_dwordx4 v[220:223], v[118:119], off
	s_branch .LBB0_566
; #define LAS __attribute__((address_space(3)))
; DI unsigned f2bf(float f) { unsigned u = __builtin_bit_cast(unsigned, f); return (u + 0x7fffu + ((u >> 16) & 1u)) >> 16; }
; DI f32x4 mma16(bf16x8 a, bf16x8 b, f32x4 c) { return __builtin_amdgcn_mfma_f32_16x16x32_bf16(a, b, c, 0, 0, 0); }
; DI v4u pack8(const float (&f)[8]) { v4u o; o.x = pk2(f[0], f[1]); o.y = pk2(f[2], f[3]); o.z = pk2(f[4], f[5]); o.w = pk2(f[6], f[7]); return o; }
; DI void gla_item(KA a, const int l, LAS unsigned char* lds, const int item) {
;     ...
;                 qo[e] = q8[e] * 0.125f * __expf(bv); ko[e] = k8[e] * __expf(-bv);
;                 KhT[k * PA + t] = (bf16)f2bf(k8[e] * __expf(tot - bv)); VT[k * PA + t] = (bf16)f2bf(v8[e]);
;                 if (t == 63) DEC[k] = __expf(tot); }
;             *(LAS v4u*)(Qt + t * PA + 8 * kg) = pack8(qo); *(LAS v4u*)(Kt + t * PA + 8 * kg) = pack8(ko);
;         }
;         __syncthreads();
;         f32x4 ao[2] = {ZERO4, ZERO4};
;         {
; #pragma unroll
;             for (int ks = 0; ks < 2; ++ks) { const bf16x8 aq = *(const LAS bf16x8*)(Qt + (16 * rt + fr) * PA + ks * 32 + fq * 8);
; #pragma unroll
;                 for (int i = 0; i < 2; ++i) { const bf16x8 bs = *(const LAS bf16x8*)(ST + (16 * (cp + i) + fr) * PA + ks * 32 + fq * 8); ao[i] = mma16(aq, bs, ao[i]); } }
;             f32x4 pp[2] = {ZERO4, ZERO4};
; #pragma unroll
;             for (int ks = 0; ks < 2; ++ks) { const bf16x8 aq = *(const LAS bf16x8*)(Qt + (16 * rt + fr) * PA + ks * 32 + fq * 8);
; #pragma unroll
;                 for (int i = 0; i < 2; ++i) { const bf16x8 bk = *(const LAS bf16x8*)(Kt + (16 * (cp + i) + fr) * PA + ks * 32 + fq * 8); pp[i] = mma16(aq, bk, pp[i]); } }
; #pragma unroll
;             for (int i = 0; i < 2; ++i)
; #pragma unroll
;                 for (int j = 0; j < 4; ++j) { const int tr = 16 * rt + 4 * fq + j, sc = 16 * (cp + i) + fr; Pm[tr * PA + sc] = (bf16)f2bf(sc <= tr ? pp[i][j] : 0.f); }
;         }
;         __syncthreads();
.LBB0_565:
	s_or_b64 exec, exec, s[0:1]
	v_mul_f32_e32 v43, 0x3fb8aa3b, v54
	v_mul_f32_e32 v54, 0xbfb8aa3b, v54
	v_exp_f32_e32 v54, v54
	v_lshlrev_b32_e32 v55, 16, v39
	v_and_b32_e32 v39, 0xffff0000, v39
	v_exp_f32_e32 v43, v43
	v_mul_f32_e32 v42, v54, v42
	v_mul_f32_e32 v54, 0x3fb8aa3b, v56
	v_exp_f32_e32 v54, v54
	v_mul_f32_e32 v39, 0x3e000000, v39
	v_mul_f32_e32 v55, 0x3e000000, v55
	v_mul_f32_e32 v43, v55, v43
	v_mul_f32_e32 v39, v39, v54
	v_mul_f32_e32 v54, 0x3fb8aa3b, v52
	v_mul_f32_e32 v52, 0xbfb8aa3b, v52
	v_exp_f32_e32 v52, v52
	v_mul_f32_e32 v55, 0xbfb8aa3b, v56
	v_exp_f32_e32 v55, v55
	v_exp_f32_e32 v54, v54
	v_mul_f32_e32 v41, v52, v41
	v_mul_f32_e32 v52, 0x3fb8aa3b, v53
	v_exp_f32_e32 v52, v52
	v_mul_f32_e32 v47, v55, v47
	v_lshlrev_b32_e32 v55, 16, v38
	v_and_b32_e32 v38, 0xffff0000, v38
	v_mul_f32_e32 v38, 0x3e000000, v38
	v_mul_f32_e32 v38, v38, v52
	v_mul_f32_e32 v52, 0x3fb8aa3b, v50
	v_mul_f32_e32 v50, 0xbfb8aa3b, v50
	v_exp_f32_e32 v50, v50
	v_mul_f32_e32 v53, 0xbfb8aa3b, v53
	v_exp_f32_e32 v53, v53
	v_exp_f32_e32 v52, v52
	v_mul_f32_e32 v40, v50, v40
	v_mul_f32_e32 v50, 0x3fb8aa3b, v51
	v_exp_f32_e32 v50, v50
	v_mul_f32_e32 v46, v53, v46
	v_lshlrev_b32_e32 v53, 16, v37
	v_mul_f32_e32 v51, 0xbfb8aa3b, v51
	v_and_b32_e32 v37, 0xffff0000, v37
	v_exp_f32_e32 v51, v51
	v_mul_f32_e32 v37, 0x3e000000, v37
	v_mul_f32_e32 v37, v37, v50
	v_mul_f32_e32 v50, 0x3fb8aa3b, v48
	v_exp_f32_e32 v50, v50
	v_mul_f32_e32 v45, v51, v45
	v_lshlrev_b32_e32 v51, 16, v36
	v_mul_f32_e32 v51, 0x3e000000, v51
	v_mul_f32_e32 v50, v51, v50
	v_mul_f32_e32 v51, 0x3fb8aa3b, v49
	v_mul_f32_e32 v48, 0xbfb8aa3b, v48
	v_exp_f32_e32 v51, v51
	v_mul_f32_e32 v49, 0xbfb8aa3b, v49
	v_exp_f32_e32 v48, v48
	v_exp_f32_e32 v49, v49
	v_and_b32_e32 v36, 0xffff0000, v36
	v_mul_f32_e32 v55, 0x3e000000, v55
	v_mul_f32_e32 v53, 0x3e000000, v53
	v_mul_f32_e32 v36, 0x3e000000, v36
	v_mul_f32_e32 v54, v55, v54
	v_mul_f32_e32 v52, v53, v52
	v_mul_f32_e32 v36, v36, v51
	v_mul_f32_e32 v48, v48, v170
	v_mul_f32_e32 v44, v49, v44
	v_cvt_pk_bf16_f32 v36, v50, v36
	v_cvt_pk_bf16_f32 v37, v52, v37
	v_cvt_pk_bf16_f32 v38, v54, v38
	v_cvt_pk_bf16_f32 v39, v43, v39
	ds_write_b128 v140, v[36:39] offset:40960
	v_cvt_pk_bf16_f32 v36, v48, v44
	v_cvt_pk_bf16_f32 v37, v40, v45
	v_cvt_pk_bf16_f32 v38, v41, v46
	v_cvt_pk_bf16_f32 v39, v42, v47
	ds_write_b128 v140, v[36:39] offset:50176
	s_waitcnt lgkmcnt(0)
	s_barrier
	ds_read_b128 v[36:39], v142 offset:40960
	ds_read_b128 v[48:51], v142 offset:41024
	v_add_u32_e32 v52, v143, v159
	ds_read_b128 v[40:43], v52
	v_add_u32_e32 v60, v143, v160
	ds_read_b128 v[44:47], v60
	ds_read_b128 v[52:55], v52 offset:64
	s_waitcnt lgkmcnt(2)
	v_mfma_f32_16x16x32_bf16 v[40:43], v[36:39], v[40:43], 0
	v_add_u32_e32 v61, v141, v159
	v_add_u32_e32 v62, v141, v160
	ds_read_b128 v[56:59], v62 offset:50176
	s_waitcnt lgkmcnt(1)
	v_mfma_f32_16x16x32_bf16 v[40:43], v[48:51], v[52:55], v[40:43]
	ds_read_b128 v[52:55], v61 offset:50176
	s_movk_i32 s0, 0x7fff
	v_add_u32_e32 v64, v145, v159
	v_mfma_f32_16x16x32_bf16 v[44:47], v[36:39], v[44:47], 0
	s_add_u32 s4, s4, 0x70000
	s_addc_u32 s5, s5, 0
	s_cmp_lg_u32 s4, 0xe00000
	s_waitcnt lgkmcnt(0)
	v_mfma_f32_16x16x32_bf16 v[52:55], v[36:39], v[52:55], 0
	v_mfma_f32_16x16x32_bf16 v[36:39], v[36:39], v[56:59], 0
	ds_read_b128 v[56:59], v61 offset:50240
	s_waitcnt lgkmcnt(0)
	v_mfma_f32_16x16x32_bf16 v[52:55], v[48:51], v[56:59], v[52:55]
	ds_read_b128 v[56:59], v62 offset:50240
	ds_read_b128 v[60:63], v60 offset:64
	s_waitcnt lgkmcnt(1)
	v_mfma_f32_16x16x32_bf16 v[36:39], v[48:51], v[56:59], v[36:39]
	s_nop 3
	v_cndmask_b32_e64 v52, v52, 0, s[58:59]
	v_bfe_u32 v56, v52, 16, 1
	v_add3_u32 v52, v52, v56, s0
	ds_write_b16_d16_hi v167, v52
	v_cndmask_b32_e64 v52, v53, 0, s[60:61]
	v_bfe_u32 v53, v52, 16, 1
	v_add3_u32 v52, v52, v53, s0
	ds_write_b16_d16_hi v167, v52 offset:144
	v_cndmask_b32_e64 v52, v54, 0, s[62:63]
	v_bfe_u32 v53, v52, 16, 1
	v_add3_u32 v52, v52, v53, s0
	ds_write_b16_d16_hi v167, v52 offset:288
	v_cndmask_b32_e64 v52, v55, 0, s[64:65]
	v_bfe_u32 v53, v52, 16, 1
	v_add3_u32 v52, v52, v53, s0
	v_cndmask_b32_e64 v36, v36, 0, s[66:67]
	ds_write_b16_d16_hi v167, v52 offset:432
	v_bfe_u32 v52, v36, 16, 1
	v_add3_u32 v36, v36, v52, s0
	ds_write_b16_d16_hi v168, v36
	v_cndmask_b32_e64 v36, v37, 0, s[68:69]
	v_bfe_u32 v37, v36, 16, 1
	v_add3_u32 v36, v36, v37, s0
	ds_write_b16_d16_hi v168, v36 offset:144
	v_cndmask_b32_e64 v36, v38, 0, s[70:71]
	v_bfe_u32 v37, v36, 16, 1
	v_add3_u32 v36, v36, v37, s0
	ds_write_b16_d16_hi v168, v36 offset:288
	v_cndmask_b32_e64 v36, v39, 0, s[2:3]
	v_bfe_u32 v37, v36, 16, 1
	v_add3_u32 v36, v36, v37, s0
	ds_write_b16_d16_hi v168, v36 offset:432
	s_waitcnt lgkmcnt(0)
	s_barrier
; #define LAS __attribute__((address_space(3)))
; DI f32x4 mma16(bf16x8 a, bf16x8 b, f32x4 c) { return __builtin_amdgcn_mfma_f32_16x16x32_bf16(a, b, c, 0, 0, 0); }
; DI void gla_item(KA a, const int l, LAS unsigned char* lds, const int item) {
;     ...
;         {
; #pragma unroll
;             for (int ks = 0; ks < 2; ++ks) { const bf16x8 ap = *(const LAS bf16x8*)(Pm + (16 * rt + fr) * PA + ks * 32 + fq * 8); const bf16x8 ak = *(const LAS bf16x8*)(KhT + (16 * rt + fr) * PA + ks * 32 + fq * 8);
;                 f32x4 u[2];
; #pragma unroll
;                 for (int i = 0; i < 2; ++i) { const bf16x8 bv = *(const LAS bf16x8*)(VT + (16 * (cp + i) + fr) * PA + ks * 32 + fq * 8); ao[i] = mma16(ap, bv, ao[i]);
;                     if (ks == 0) { f32x4 sd; for (int j = 0; j < 4; ++j) sd[j] = S[i][j] * DEC[16 * rt + 4 * fq + j]; S[i] = sd; }
;                     S[i] = mma16(ak, bv, S[i]); }
;             }
; #pragma unroll
;             for (int i = 0; i < 2; ++i)
; #pragma unroll
;                 for (int j = 0; j < 4; ++j) OUTF[(16 * rt + 4 * fq + j) * 64 + 16 * (cp + i) + fr] = ao[i][j];
;         }
;         __syncthreads();
	ds_read_b128 v[36:39], v144
	v_mfma_f32_16x16x32_bf16 v[44:47], v[48:51], v[60:63], v[44:47]
	ds_read_b128 v[48:51], v64
	v_add_u32_e32 v60, v145, v160
	ds_read_b128 v[52:55], v60
	ds_read_b128 v[56:59], v142 offset:59392
	s_waitcnt lgkmcnt(2)
	v_mfma_f32_16x16x32_bf16 v[40:43], v[36:39], v[48:51], v[40:43]
	v_and_b32_e32 v61, 0xffff0000, v3
	v_and_b32_e32 v63, 0xffff0000, v2
	s_mov_b32 s0, 0xf800000
	s_waitcnt lgkmcnt(1)
	v_mfma_f32_16x16x32_bf16 v[36:39], v[36:39], v[52:55], v[44:47]
	v_lshlrev_b32_e32 v62, 16, v2
	v_mul_f32_e32 v2, 0xbfb8aa3b, v62
	v_exp_f32_e32 v2, v2
	ds_read_b128 v[44:47], v169 offset:39168
	v_add_f32_e32 v2, 1.0, v2
	v_rcp_f32_e32 v2, v2
	s_waitcnt lgkmcnt(0)
	v_pk_mul_f32 v[32:33], v[32:33], v[44:45]
	v_pk_mul_f32 v[34:35], v[34:35], v[46:47]
	v_pk_mul_f32 v[28:29], v[28:29], v[44:45]
	v_pk_mul_f32 v[30:31], v[30:31], v[46:47]
	v_mfma_f32_16x16x32_bf16 v[32:35], v[56:59], v[48:51], v[32:35]
	ds_read_b128 v[48:51], v144 offset:64
	ds_read_b128 v[44:47], v64 offset:64
	v_mfma_f32_16x16x32_bf16 v[28:31], v[56:59], v[52:55], v[28:31]
	ds_read_b128 v[52:55], v142 offset:59456
	s_waitcnt lgkmcnt(1)
	v_mfma_f32_16x16x32_bf16 v[40:43], v[48:51], v[44:47], v[40:43]
	s_waitcnt lgkmcnt(0)
	v_mfma_f32_16x16x32_bf16 v[32:35], v[52:55], v[44:47], v[32:35]
	ds_read_b128 v[44:47], v60 offset:64
	v_lshlrev_b32_e32 v60, 16, v3
	s_waitcnt lgkmcnt(0)
	v_mfma_f32_16x16x32_bf16 v[36:39], v[48:51], v[44:47], v[36:39]
	v_mfma_f32_16x16x32_bf16 v[28:31], v[52:55], v[44:47], v[28:31]
	v_add_u32_e32 v44, v162, v161
	ds_write_b32 v44, v40 offset:16384
	v_add_u32_e32 v40, v162, v163
	ds_write_b32 v40, v41 offset:16384
	v_add_u32_e32 v40, v162, v164
	ds_write_b32 v40, v42 offset:16384
	v_add_u32_e32 v40, v162, v165
	ds_write_b32 v40, v43 offset:16384
	v_add_u32_e32 v40, v166, v161
	ds_write_b32 v40, v36 offset:16384
	v_add_u32_e32 v36, v166, v163
	ds_write_b32 v36, v37 offset:16384
	v_add_u32_e32 v36, v166, v164
	ds_write_b32 v36, v38 offset:16384
	v_add_u32_e32 v36, v166, v165
	ds_write_b32 v36, v39 offset:16384
	v_cvt_pk_bf16_f32 v36, v32, v33
	v_cvt_pk_bf16_f32 v37, v34, v35
	v_add_u32_e32 v38, v146, v159
	s_waitcnt lgkmcnt(0)
	s_barrier
; #define LAS __attribute__((address_space(3)))
; DI unsigned pk2(float lo, float hi) { const f32x2 v = {lo, hi}; const bf16x2_t b = __builtin_convertvector(v, bf16x2_t); return __builtin_bit_cast(unsigned, b); }
; DI float sigmoidf_(float x) { return __builtin_amdgcn_rcpf(1.f + __expf(-x)); }
; DI void unpack8(const v4u u, float (&f)[8]) { f[0] = bflo(u.x); f[1] = bfhi(u.x); f[2] = bflo(u.y); f[3] = bfhi(u.y); f[4] = bflo(u.z); f[5] = bfhi(u.z); f[6] = bflo(u.w); f[7] = bfhi(u.w); }
; DI v4u pack8(const float (&f)[8]) { v4u o; o.x = pk2(f[0], f[1]); o.y = pk2(f[2], f[3]); o.z = pk2(f[4], f[5]); o.w = pk2(f[6], f[7]); return o; }
; DI void gla_item(KA a, const int l, LAS unsigned char* lds, const int item) {
;     ...
;         {
; #pragma unroll
;             for (int i = 0; i < 2; ++i) { v2u p; p.x = pk2(S[i][0], S[i][1]); p.y = pk2(S[i][2], S[i][3]); *(LAS v2u*)(ST + (16 * (cp + i) + fr) * PA + 16 * rt + 4 * fq) = p; }
;             float x[8], sm = 0.f;
; #pragma unroll
;             for (int e = 0; e < 8; ++e) { x[e] = OUTF[t * 64 + 8 * kg + e]; sm += x[e]; }
;             sm += __shfl_xor(sm, 1); sm += __shfl_xor(sm, 2); sm += __shfl_xor(sm, 4);
;             const float mean = sm * (1.f / 64.f); float qv = 0.f;
; #pragma unroll
;             for (int e = 0; e < 8; ++e) { x[e] -= mean; qv += x[e] * x[e]; }
;             qv += __shfl_xor(qv, 1); qv += __shfl_xor(qv, 2); qv += __shfl_xor(qv, 4);
;             const float rstd = 1.f / sqrtf(qv * (1.f / 64.f) + LN_EPS);
;             float g8[8], o[8]; unpack8(cg_, g8);
; #pragma unroll
;             for (int e = 0; e < 8; ++e) { const float yv = x[e] * rstd * lnw[8 * kg + e] + lnb[8 * kg + e]; o[e] = yv * g8[e] * sigmoidf_(g8[e]); }
;             *(v4u*)(act + (tb + t) * D + hh * 64 + 8 * kg) = pack8(o);
	ds_write_b64 v38, v[36:37]
	v_cvt_pk_bf16_f32 v36, v28, v29
	v_cvt_pk_bf16_f32 v37, v30, v31
	v_add_u32_e32 v38, v146, v160
	ds_write_b64 v38, v[36:37]
	ds_read_b128 v[36:39], v138 offset:16384
	ds_read_b128 v[40:43], v138 offset:16400
	s_waitcnt lgkmcnt(1)
	v_add_f32_e32 v3, 0, v36
	v_add_f32_e32 v3, v3, v37
	v_add_f32_e32 v3, v3, v38
	v_add_f32_e32 v3, v3, v39
	s_waitcnt lgkmcnt(0)
	v_add_f32_e32 v3, v3, v40
	v_add_f32_e32 v3, v3, v41
	v_add_f32_e32 v3, v3, v42
	v_add_f32_e32 v3, v3, v43
	s_nop 1
	s_waitcnt lgkmcnt(0)
	v_add_f32_dpp v3, v3, v3 quad_perm:[1,0,3,2] row_mask:0xf bank_mask:0xf
	v_mul_f32_e32 v52, 0xbfb8aa3b, v63
	v_exp_f32_e32 v65, v52
	s_nop 1
	s_waitcnt lgkmcnt(0)
	v_add_f32_dpp v66, v3, v3 quad_perm:[2,3,0,1] row_mask:0xf bank_mask:0xf
	s_nop 1
	v_add_f32_e32 v3, 1.0, v65
	v_lshlrev_b32_e32 v64, 16, v1
	v_and_b32_e32 v65, 0xffff0000, v1
	v_rcp_f32_e32 v3, v3
	s_waitcnt lgkmcnt(0)
	v_add_f32_dpp v1, v66, v66 row_half_mirror row_mask:0xf bank_mask:0xf
	v_mul_f32_e32 v66, 0x3c800000, v1
	v_pk_add_f32 v[36:37], v[36:37], v[66:67] op_sel_hi:[1,0] neg_lo:[0,1] neg_hi:[0,1]
	v_pk_add_f32 v[38:39], v[38:39], v[66:67] op_sel_hi:[1,0] neg_lo:[0,1] neg_hi:[0,1]
	v_pk_mul_f32 v[68:69], v[36:37], v[36:37]
	v_pk_mul_f32 v[70:71], v[38:39], v[38:39]
	v_add_f32_e32 v1, v68, v69
	v_pk_add_f32 v[40:41], v[40:41], v[66:67] op_sel_hi:[1,0] neg_lo:[0,1] neg_hi:[0,1]
	v_add_f32_e32 v1, v70, v1
	v_pk_mul_f32 v[72:73], v[40:41], v[40:41]
	v_add_f32_e32 v1, v71, v1
	v_pk_add_f32 v[42:43], v[42:43], v[66:67] op_sel_hi:[1,0] neg_lo:[0,1] neg_hi:[0,1]
	v_add_f32_e32 v1, v72, v1
	v_pk_mul_f32 v[66:67], v[42:43], v[42:43]
	v_add_f32_e32 v1, v73, v1
	v_add_f32_e32 v1, v66, v1
	v_add_f32_e32 v1, v67, v1
	s_nop 1
	v_mul_f32_e32 v67, 0xbfb8aa3b, v64
	v_mul_f32_e32 v68, 0xbfb8aa3b, v65
	v_exp_f32_e32 v67, v67
	v_exp_f32_e32 v68, v68
	s_waitcnt lgkmcnt(0)
	v_add_f32_dpp v1, v1, v1 quad_perm:[1,0,3,2] row_mask:0xf bank_mask:0xf
	s_nop 1
	v_add_f32_e32 v66, 1.0, v67
	v_add_f32_e32 v67, 1.0, v68
	v_lshlrev_b32_e32 v68, 16, v0
	v_rcp_f32_e32 v66, v66
	s_waitcnt lgkmcnt(0)
	v_add_f32_dpp v1, v1, v1 quad_perm:[2,3,0,1] row_mask:0xf bank_mask:0xf
	s_nop 1
	v_and_b32_e32 v69, 0xffff0000, v0
	v_mul_f32_e32 v71, 0xbfb8aa3b, v69
	v_exp_f32_e32 v71, v71
	v_mul_f32_e32 v0, 0xbfb8aa3b, v68
	s_waitcnt lgkmcnt(0)
	v_add_f32_dpp v1, v1, v1 row_half_mirror row_mask:0xf bank_mask:0xf
	v_fmamk_f32 v1, v1, 0x3c800000, v235
	v_mul_f32_e32 v70, 0x4f800000, v1
	v_cmp_gt_f32_e32 vcc, s0, v1
	v_exp_f32_e32 v0, v0
	v_rcp_f32_e32 v67, v67
	v_cndmask_b32_e32 v1, v1, v70, vcc
	v_sqrt_f32_e32 v70, v1
	v_add_f32_e32 v0, 1.0, v0
	v_rcp_f32_e32 v0, v0
	v_add_u32_e32 v72, -1, v70
	v_fma_f32 v73, -v72, v70, v1
	v_cmp_ge_f32_e64 s[0:1], 0, v73
	v_add_u32_e32 v73, 1, v70
	s_nop 0
	v_cndmask_b32_e64 v72, v70, v72, s[0:1]
	v_fma_f32 v70, -v73, v70, v1
	v_cmp_lt_f32_e64 s[0:1], 0, v70
	s_nop 1
	v_cndmask_b32_e64 v70, v72, v73, s[0:1]
	v_mul_f32_e32 v72, 0x37800000, v70
	v_cndmask_b32_e32 v70, v70, v72, vcc
	v_cmp_class_f32_e32 vcc, v1, v234
	s_nop 1
	v_cndmask_b32_e32 v70, v70, v1, vcc
	v_div_scale_f32 v72, s[0:1], v70, v70, 1.0
	v_rcp_f32_e32 v73, v72
	v_add_f32_e32 v1, 1.0, v71
	v_rcp_f32_e32 v1, v1
	s_mov_b64 s[0:1], 0x20000
	v_fma_f32 v71, -v72, v73, 1.0
	v_fmac_f32_e32 v73, v71, v73
	v_div_scale_f32 v71, vcc, 1.0, v70, 1.0
	v_mul_f32_e32 v74, v71, v73
	v_fma_f32 v75, -v72, v74, v71
	v_fmac_f32_e32 v74, v75, v73
	v_fma_f32 v71, -v72, v74, v71
	v_div_fmas_f32 v71, v71, v73, v74
	v_div_fixup_f32 v70, v71, v70, 1.0
	v_pk_mul_f32 v[36:37], v[36:37], v[70:71] op_sel_hi:[1,0]
	s_waitcnt vmcnt(0)
	v_pk_fma_f32 v[36:37], v[212:213], v[36:37], v[220:221]
	s_nop 0
	v_pk_mul_f32 v[36:37], v[36:37], v[68:69]
	s_nop 0
	v_pk_mul_f32 v[0:1], v[0:1], v[36:37]
	v_pk_mul_f32 v[36:37], v[38:39], v[70:71] op_sel_hi:[1,0]
	v_pk_mul_f32 v[38:39], v[40:41], v[70:71] op_sel_hi:[1,0]
	v_mul_f32_e32 v40, 0xbfb8aa3b, v60
	v_mul_f32_e32 v41, 0xbfb8aa3b, v61
	v_exp_f32_e32 v40, v40
	v_exp_f32_e32 v41, v41
	v_pk_fma_f32 v[38:39], v[208:209], v[38:39], v[216:217]
	v_pk_fma_f32 v[36:37], v[214:215], v[36:37], v[222:223]
	v_pk_mul_f32 v[38:39], v[38:39], v[62:63]
	v_pk_mul_f32 v[36:37], v[36:37], v[64:65]
	v_pk_mul_f32 v[2:3], v[2:3], v[38:39]
	v_add_f32_e32 v38, 1.0, v40
	v_add_f32_e32 v39, 1.0, v41
	v_rcp_f32_e32 v38, v38
	v_rcp_f32_e32 v39, v39
	v_pk_mul_f32 v[40:41], v[42:43], v[70:71] op_sel_hi:[1,0]
	v_pk_mul_f32 v[36:37], v[66:67], v[36:37]
	v_pk_fma_f32 v[40:41], v[210:211], v[40:41], v[218:219]
	v_cvt_pk_bf16_f32 v0, v0, v1
	v_pk_mul_f32 v[40:41], v[40:41], v[60:61]
	v_cvt_pk_bf16_f32 v1, v36, v37
	v_pk_mul_f32 v[38:39], v[38:39], v[40:41]
	v_cvt_pk_bf16_f32 v2, v2, v3
	v_cvt_pk_bf16_f32 v3, v38, v39
	global_store_dwordx4 v[120:121], v[0:3], off
	v_mov_b64_e32 v[38:39], v[18:19]
	v_mov_b64_e32 v[46:47], v[14:15]
	v_mov_b64_e32 v[42:43], v[10:11]
	v_mov_b64_e32 v[0:1], v[4:5]
	v_mov_b64_e32 v[54:55], v[26:27]
	v_mov_b64_e32 v[50:51], v[22:23]
	v_lshl_add_u64 v[120:121], v[120:121], 0, s[0:1]
	v_mov_b64_e32 v[36:37], v[16:17]
	v_mov_b64_e32 v[44:45], v[12:13]
	v_mov_b64_e32 v[40:41], v[8:9]
	v_mov_b64_e32 v[2:3], v[6:7]
	v_mov_b64_e32 v[52:53], v[24:25]
	v_mov_b64_e32 v[48:49], v[20:21]
	s_cbranch_scc0 .LBB0_584
